# GLU prologue also L2-prefetches the first 16 Y slabs of the first out-proj tile (issued before the staging loads)
# baseline (speedup 1.0000x reference)
; template <int NT2>
; DI void glu_prologue(const Params& p, char* lds, int l, int tile0, int tile1) {
;     ...
;     __syncthreads();
; #pragma unroll
;     for (int tt = 0; tt < NT2; ++tt) {
;         const int tile = tt ? tile1 : tile0;
;         char* Ys = lds + tt * 33792;
;         const bf16_t* ysg = WS_PTR(const bf16_t, OFF_YS) + (size_t)tile * 64 * 256;
; #pragma unroll
;         for (int i = 0; i < 4; ++i) {
;             const int idx = tid + NTHR * i, row = idx >> 5, c16 = idx & 31;
;             *(u32x4*)(Ys + row * 528 + c16 * 16) = *(const u32x4*)(ysg + (size_t)row * 256 + c16 * 8);
;         }
;     }
;     __syncthreads();
;     f32x4 acc[NT2][4][2];
; #pragma unroll
;     for (int tt = 0; tt < NT2; ++tt)
; #pragma unroll
;         for (int mt = 0; mt < 4; ++mt) { acc[tt][mt][0] = (f32x4){0.f, 0.f, 0.f, 0.f}; acc[tt][mt][1] = (f32x4){0.f, 0.f, 0.f, 0.f}; }
;     const bf16_t* Wg = WS_PTR(const bf16_t, OFF_WGLU) + (size_t)l * 65536;
; #pragma unroll 2
;     for (int ks = 0; ks < 8; ++ks) {
;         bf16x8 bb[2];
; #pragma unroll
;         for (int nt = 0; nt < 2; ++nt) bb[nt] = *(const bf16x8*)(Wg + (wid * 32 + nt * 16 + l15) * 256 + 32 * ks + 8 * quad);
.LBB0_90:
	s_and_b64 vcc, exec, s[6:7]
	s_cbranch_vccz .LBB0_94
	s_ashr_i32 s35, s34, 31
	v_mov_b32_e32 v78, v212
	s_lshl_b64 s[8:9], s[34:35], 15
	v_readlane_b32 s40, v244, 46
	s_add_u32 s6, s40, s8
	v_lshlrev_b32_e32 v0, 4, v78
	v_ashrrev_i32_e32 v8, 5, v78
	v_readlane_b32 s47, v244, 47
	v_and_b32_e32 v0, 0x1f0, v0
	v_ashrrev_i32_e32 v9, 31, v8
	s_addc_u32 s7, s47, s9
	v_lshlrev_b64 v[10:11], 9, v[8:9]
	v_lshl_add_u64 v[12:13], s[6:7], 0, v[0:1]
	v_lshl_add_u64 v[2:3], v[12:13], 0, v[10:11]
	s_barrier
	v_lshrrev_b32_e32 v247, 5, v212
	v_add_u32_e32 v247, s33, v247
	v_and_b32_e32 v247, 31, v247
	v_and_b32_e32 v246, 31, v212
	v_lshlrev_b32_e32 v246, 7, v246
	v_lshl_or_b32 v247, v247, 12, v246
	s_lshl_b32 s94, s34, 17
	s_add_u32 s94, s54, s94
	s_addc_u32 s95, s55, 0
	global_load_dword v247, v247, s[94:95]
	global_load_dwordx4 v[172:175], v[2:3], off
	v_add_u32_e32 v6, 0, v0
	s_movk_i32 s46, 0x210
	v_mad_u64_u32 v[8:9], s[6:7], v8, s46, v[6:7]
	s_ashr_i32 s49, s48, 31
	v_and_b32_e32 v84, 15, v78
	v_ashrrev_i32_e32 v76, 6, v78
	v_bfe_u32 v79, v78, 4, 2
	v_mul_u32_u24_e32 v82, 0x210, v84
	v_add_u32_e32 v2, 0x200, v78
	v_ashrrev_i32_e32 v14, 5, v2
	v_ashrrev_i32_e32 v15, 31, v14
	v_lshlrev_b64 v[16:17], 9, v[14:15]
	v_lshl_add_u64 v[2:3], v[12:13], 0, v[16:17]
	global_load_dwordx4 v[176:179], v[2:3], off
	v_mad_u64_u32 v[14:15], s[6:7], v14, s46, v[6:7]
	v_add_u32_e32 v2, 0x400, v78
	v_ashrrev_i32_e32 v18, 5, v2
	v_ashrrev_i32_e32 v19, 31, v18
	v_lshlrev_b64 v[20:21], 9, v[18:19]
	v_lshl_add_u64 v[2:3], v[12:13], 0, v[20:21]
	global_load_dwordx4 v[180:183], v[2:3], off
	v_mad_u64_u32 v[18:19], s[6:7], v18, s46, v[6:7]
	v_add_u32_e32 v2, 0x600, v78
	v_ashrrev_i32_e32 v22, 5, v2
	v_ashrrev_i32_e32 v23, 31, v22
	v_lshlrev_b64 v[24:25], 9, v[22:23]
	v_lshl_add_u64 v[2:3], v[12:13], 0, v[24:25]
	global_load_dwordx4 v[184:187], v[2:3], off
	v_mad_u64_u32 v[6:7], s[6:7], v22, s46, v[6:7]
	s_lshl_b64 s[6:7], s[48:49], 15
	s_add_u32 s46, s40, s6
	s_addc_u32 s47, s47, s7
	v_lshl_add_u64 v[12:13], s[46:47], 0, v[0:1]
	v_lshlrev_b32_e32 v0, 8, v84
	s_mov_b64 s[46:47], 0
	v_lshl_add_u64 v[2:3], v[12:13], 0, v[10:11]
	global_load_dwordx4 v[188:191], v[2:3], off
	v_lshl_add_u64 v[2:3], v[12:13], 0, v[16:17]
	global_load_dwordx4 v[192:195], v[2:3], off
	v_lshl_add_u64 v[2:3], v[12:13], 0, v[20:21]
	global_load_dwordx4 v[196:199], v[2:3], off
	v_lshl_add_u64 v[2:3], v[12:13], 0, v[24:25]
	global_load_dwordx4 v[200:203], v[2:3], off
	v_lshl_or_b32 v2, v76, 13, v0
	v_ashrrev_i32_e32 v3, 31, v2
	v_lshlrev_b32_e32 v4, 4, v79
	v_lshlrev_b64 v[2:3], 1, v[2:3]
	v_or_b32_e32 v2, v2, v4
	v_lshl_add_u64 v[66:67], s[30:31], 0, v[2:3]
	v_add_co_u32_e32 v80, vcc, s87, v66
	s_nop 1
	v_addc_co_u32_e32 v81, vcc, 0, v67, vcc
	v_add_co_u32_e32 v102, vcc, s86, v66
	s_nop 1
	v_addc_co_u32_e32 v103, vcc, 0, v67, vcc
	global_load_dwordx4 v[104:107], v[80:81], off
	global_load_dwordx4 v[108:111], v[102:103], off
	global_load_dwordx4 v[112:115], v[80:81], off offset:64
	global_load_dwordx4 v[116:119], v[102:103], off offset:64
	global_load_dwordx4 v[120:123], v[80:81], off offset:128
	global_load_dwordx4 v[124:127], v[102:103], off offset:128
	global_load_dwordx4 v[128:131], v[80:81], off offset:192
	global_load_dwordx4 v[132:135], v[102:103], off offset:192
	global_load_dwordx4 v[140:143], v[80:81], off offset:256
	global_load_dwordx4 v[144:147], v[102:103], off offset:256
	global_load_dwordx4 v[148:151], v[80:81], off offset:320
	global_load_dwordx4 v[152:155], v[102:103], off offset:320
	global_load_dwordx4 v[156:159], v[80:81], off offset:384
	global_load_dwordx4 v[160:163], v[102:103], off offset:384
	global_load_dwordx4 v[164:167], v[80:81], off offset:448
	global_load_dwordx4 v[168:171], v[102:103], off offset:448
	s_waitcnt vmcnt(23)
	ds_write_b128 v8, v[172:175]
	s_waitcnt vmcnt(22)
	ds_write_b128 v14, v[176:179]
	s_waitcnt vmcnt(21)
	ds_write_b128 v18, v[180:183]
	s_waitcnt vmcnt(20)
	ds_write_b128 v6, v[184:187]
	s_waitcnt vmcnt(19)
	ds_write_b128 v8, v[188:191] offset:33792
	s_waitcnt vmcnt(18)
	ds_write_b128 v14, v[192:195] offset:33792
	s_waitcnt vmcnt(17)
	ds_write_b128 v18, v[196:199] offset:33792
	s_waitcnt vmcnt(16)
	ds_write_b128 v6, v[200:203] offset:33792
	v_mov_b32_e32 v2, 0
	v_add3_u32 v77, v82, v4, 0
	v_mov_b32_e32 v3, v2
	v_mov_b32_e32 v4, v2
	v_mov_b32_e32 v5, v2
	v_mov_b32_e32 v14, v2
	v_mov_b32_e32 v15, v2
	v_mov_b32_e32 v16, v2
	v_mov_b32_e32 v17, v2
	v_mov_b32_e32 v18, v2
	v_mov_b32_e32 v19, v2
	v_mov_b32_e32 v20, v2
	v_mov_b32_e32 v21, v2
	v_mov_b32_e32 v22, v2
	v_mov_b32_e32 v23, v2
	v_mov_b32_e32 v24, v2
	v_mov_b32_e32 v25, v2
	v_mov_b32_e32 v26, v2
	v_mov_b32_e32 v27, v2
	v_mov_b32_e32 v28, v2
	v_mov_b32_e32 v29, v2
	v_mov_b32_e32 v34, v2
	v_mov_b32_e32 v35, v2
	v_mov_b32_e32 v36, v2
	v_mov_b32_e32 v37, v2
	v_mov_b32_e32 v30, v2
	v_mov_b32_e32 v31, v2
	v_mov_b32_e32 v32, v2
	v_mov_b32_e32 v33, v2
	v_mov_b32_e32 v38, v2
	v_mov_b32_e32 v39, v2
	v_mov_b32_e32 v40, v2
	v_mov_b32_e32 v41, v2
	v_mov_b32_e32 v42, v2
	v_mov_b32_e32 v43, v2
	v_mov_b32_e32 v44, v2
	v_mov_b32_e32 v45, v2
	v_mov_b32_e32 v46, v2
	v_mov_b32_e32 v47, v2
	v_mov_b32_e32 v48, v2
	v_mov_b32_e32 v49, v2
	v_mov_b32_e32 v50, v2
	v_mov_b32_e32 v51, v2
	v_mov_b32_e32 v52, v2
	v_mov_b32_e32 v53, v2
	v_mov_b32_e32 v68, v2
	v_mov_b32_e32 v69, v2
	v_mov_b32_e32 v70, v2
	v_mov_b32_e32 v71, v2
	v_mov_b32_e32 v58, v2
	v_mov_b32_e32 v59, v2
	v_mov_b32_e32 v60, v2
	v_mov_b32_e32 v61, v2
	v_mov_b32_e32 v54, v2
	v_mov_b32_e32 v55, v2
	v_mov_b32_e32 v56, v2
	v_mov_b32_e32 v57, v2
	v_mov_b32_e32 v10, v2
	v_mov_b32_e32 v11, v2
	v_mov_b32_e32 v12, v2
	v_mov_b32_e32 v13, v2
	v_mov_b32_e32 v6, v2
	v_mov_b32_e32 v7, v2
	v_mov_b32_e32 v8, v2
	v_mov_b32_e32 v9, v2
	s_waitcnt lgkmcnt(0)
	s_barrier
; DI f32x4 mfma16(bf16x8 a, bf16x8 b, f32x4 c) { return __builtin_amdgcn_mfma_f32_16x16x32_bf16(a, b, c, 0, 0, 0); }
; template <int NT2>
; DI void glu_prologue(const Params& p, char* lds, int l, int tile0, int tile1) {
;     ...
; #pragma unroll 2
;     for (int ks = 0; ks < 8; ++ks) {
;         bf16x8 bb[2];
; #pragma unroll
;         for (int nt = 0; nt < 2; ++nt) bb[nt] = *(const bf16x8*)(Wg + (wid * 32 + nt * 16 + l15) * 256 + 32 * ks + 8 * quad);
; #pragma unroll
;         for (int tt = 0; tt < NT2; ++tt) {
;             const char* Ys = lds + tt * 33792;
;             bf16x8 a[4];
; #pragma unroll
;             for (int mt = 0; mt < 4; ++mt) a[mt] = *(const bf16x8*)(Ys + (mt * 16 + l15) * 528 + (32 * ks + 8 * quad) * 2);
; #pragma unroll
;             for (int mt = 0; mt < 4; ++mt)
; #pragma unroll
;                 for (int nt = 0; nt < 2; ++nt) acc[tt][mt][nt] = mfma16(bb[nt], a[mt], acc[tt][mt][nt]);
;         }
	s_waitcnt vmcnt(14)
	ds_read_b128 v[86:89], v77
	ds_read_b128 v[90:93], v77 offset:8448
	ds_read_b128 v[94:97], v77 offset:16896
	ds_read_b128 v[98:101], v77 offset:25344
	s_waitcnt lgkmcnt(3)
	v_mfma_f32_16x16x32_bf16 v[54:57], v[104:107], v[86:89], v[54:57]
	v_mfma_f32_16x16x32_bf16 v[58:61], v[108:111], v[86:89], v[58:61]
	s_waitcnt lgkmcnt(2)
	v_mfma_f32_16x16x32_bf16 v[68:71], v[104:107], v[90:93], v[68:71]
	v_mfma_f32_16x16x32_bf16 v[50:53], v[108:111], v[90:93], v[50:53]
	s_waitcnt lgkmcnt(1)
	v_mfma_f32_16x16x32_bf16 v[46:49], v[104:107], v[94:97], v[46:49]
	v_mfma_f32_16x16x32_bf16 v[42:45], v[108:111], v[94:97], v[42:45]
	s_waitcnt lgkmcnt(0)
	v_mfma_f32_16x16x32_bf16 v[38:41], v[104:107], v[98:101], v[38:41]
	v_mfma_f32_16x16x32_bf16 v[30:33], v[108:111], v[98:101], v[30:33]
	ds_read_b128 v[86:89], v77 offset:33792
	ds_read_b128 v[90:93], v77 offset:42240
	ds_read_b128 v[94:97], v77 offset:50688
	ds_read_b128 v[98:101], v77 offset:59136
	s_waitcnt lgkmcnt(3)
	v_mfma_f32_16x16x32_bf16 v[34:37], v[104:107], v[86:89], v[34:37]
	v_mfma_f32_16x16x32_bf16 v[26:29], v[108:111], v[86:89], v[26:29]
	s_waitcnt lgkmcnt(2)
	v_mfma_f32_16x16x32_bf16 v[22:25], v[104:107], v[90:93], v[22:25]
	v_mfma_f32_16x16x32_bf16 v[18:21], v[108:111], v[90:93], v[18:21]
	s_waitcnt lgkmcnt(1)
	v_mfma_f32_16x16x32_bf16 v[14:17], v[104:107], v[94:97], v[14:17]
	v_mfma_f32_16x16x32_bf16 v[2:5], v[108:111], v[94:97], v[2:5]
	s_waitcnt lgkmcnt(0)
	v_mfma_f32_16x16x32_bf16 v[10:13], v[104:107], v[98:101], v[10:13]
	v_mfma_f32_16x16x32_bf16 v[6:9], v[108:111], v[98:101], v[6:9]
	s_waitcnt vmcnt(12)
	ds_read_b128 v[86:89], v77 offset:64
	ds_read_b128 v[90:93], v77 offset:8512
	ds_read_b128 v[94:97], v77 offset:16960
	ds_read_b128 v[98:101], v77 offset:25408
	s_waitcnt lgkmcnt(3)
	v_mfma_f32_16x16x32_bf16 v[54:57], v[112:115], v[86:89], v[54:57]
	v_mfma_f32_16x16x32_bf16 v[58:61], v[116:119], v[86:89], v[58:61]
	s_waitcnt lgkmcnt(2)
	v_mfma_f32_16x16x32_bf16 v[68:71], v[112:115], v[90:93], v[68:71]
	v_mfma_f32_16x16x32_bf16 v[50:53], v[116:119], v[90:93], v[50:53]
	s_waitcnt lgkmcnt(1)
	v_mfma_f32_16x16x32_bf16 v[46:49], v[112:115], v[94:97], v[46:49]
	v_mfma_f32_16x16x32_bf16 v[42:45], v[116:119], v[94:97], v[42:45]
	s_waitcnt lgkmcnt(0)
	v_mfma_f32_16x16x32_bf16 v[38:41], v[112:115], v[98:101], v[38:41]
	v_mfma_f32_16x16x32_bf16 v[30:33], v[116:119], v[98:101], v[30:33]
	ds_read_b128 v[86:89], v77 offset:33856
	ds_read_b128 v[90:93], v77 offset:42304
	ds_read_b128 v[94:97], v77 offset:50752
	ds_read_b128 v[98:101], v77 offset:59200
	s_waitcnt lgkmcnt(3)
	v_mfma_f32_16x16x32_bf16 v[34:37], v[112:115], v[86:89], v[34:37]
	v_mfma_f32_16x16x32_bf16 v[26:29], v[116:119], v[86:89], v[26:29]
	s_waitcnt lgkmcnt(2)
	v_mfma_f32_16x16x32_bf16 v[22:25], v[112:115], v[90:93], v[22:25]
	v_mfma_f32_16x16x32_bf16 v[18:21], v[116:119], v[90:93], v[18:21]
	s_waitcnt lgkmcnt(1)
	v_mfma_f32_16x16x32_bf16 v[14:17], v[112:115], v[94:97], v[14:17]
	v_mfma_f32_16x16x32_bf16 v[2:5], v[116:119], v[94:97], v[2:5]
	s_waitcnt lgkmcnt(0)
	v_mfma_f32_16x16x32_bf16 v[10:13], v[112:115], v[98:101], v[10:13]
	v_mfma_f32_16x16x32_bf16 v[6:9], v[116:119], v[98:101], v[6:9]
	s_waitcnt vmcnt(10)
	ds_read_b128 v[86:89], v77 offset:128
	ds_read_b128 v[90:93], v77 offset:8576
	ds_read_b128 v[94:97], v77 offset:17024
	ds_read_b128 v[98:101], v77 offset:25472
	s_waitcnt lgkmcnt(3)
	v_mfma_f32_16x16x32_bf16 v[54:57], v[120:123], v[86:89], v[54:57]
	v_mfma_f32_16x16x32_bf16 v[58:61], v[124:127], v[86:89], v[58:61]
	s_waitcnt lgkmcnt(2)
	v_mfma_f32_16x16x32_bf16 v[68:71], v[120:123], v[90:93], v[68:71]
	v_mfma_f32_16x16x32_bf16 v[50:53], v[124:127], v[90:93], v[50:53]
	s_waitcnt lgkmcnt(1)
	v_mfma_f32_16x16x32_bf16 v[46:49], v[120:123], v[94:97], v[46:49]
	v_mfma_f32_16x16x32_bf16 v[42:45], v[124:127], v[94:97], v[42:45]
	s_waitcnt lgkmcnt(0)
	v_mfma_f32_16x16x32_bf16 v[38:41], v[120:123], v[98:101], v[38:41]
	v_mfma_f32_16x16x32_bf16 v[30:33], v[124:127], v[98:101], v[30:33]
	ds_read_b128 v[86:89], v77 offset:33920
	ds_read_b128 v[90:93], v77 offset:42368
	ds_read_b128 v[94:97], v77 offset:50816
	ds_read_b128 v[98:101], v77 offset:59264
	s_waitcnt lgkmcnt(3)
	v_mfma_f32_16x16x32_bf16 v[34:37], v[120:123], v[86:89], v[34:37]
	v_mfma_f32_16x16x32_bf16 v[26:29], v[124:127], v[86:89], v[26:29]
	s_waitcnt lgkmcnt(2)
	v_mfma_f32_16x16x32_bf16 v[22:25], v[120:123], v[90:93], v[22:25]
	v_mfma_f32_16x16x32_bf16 v[18:21], v[124:127], v[90:93], v[18:21]
	s_waitcnt lgkmcnt(1)
	v_mfma_f32_16x16x32_bf16 v[14:17], v[120:123], v[94:97], v[14:17]
	v_mfma_f32_16x16x32_bf16 v[2:5], v[124:127], v[94:97], v[2:5]
	s_waitcnt lgkmcnt(0)
	v_mfma_f32_16x16x32_bf16 v[10:13], v[120:123], v[98:101], v[10:13]
	v_mfma_f32_16x16x32_bf16 v[6:9], v[124:127], v[98:101], v[6:9]
	s_waitcnt vmcnt(8)
	ds_read_b128 v[86:89], v77 offset:192
	ds_read_b128 v[90:93], v77 offset:8640
	ds_read_b128 v[94:97], v77 offset:17088
	ds_read_b128 v[98:101], v77 offset:25536
	s_waitcnt lgkmcnt(3)
	v_mfma_f32_16x16x32_bf16 v[54:57], v[128:131], v[86:89], v[54:57]
	v_mfma_f32_16x16x32_bf16 v[58:61], v[132:135], v[86:89], v[58:61]
	s_waitcnt lgkmcnt(2)
	v_mfma_f32_16x16x32_bf16 v[68:71], v[128:131], v[90:93], v[68:71]
	v_mfma_f32_16x16x32_bf16 v[50:53], v[132:135], v[90:93], v[50:53]
	s_waitcnt lgkmcnt(1)
	v_mfma_f32_16x16x32_bf16 v[46:49], v[128:131], v[94:97], v[46:49]
	v_mfma_f32_16x16x32_bf16 v[42:45], v[132:135], v[94:97], v[42:45]
	s_waitcnt lgkmcnt(0)
	v_mfma_f32_16x16x32_bf16 v[38:41], v[128:131], v[98:101], v[38:41]
	v_mfma_f32_16x16x32_bf16 v[30:33], v[132:135], v[98:101], v[30:33]
	ds_read_b128 v[86:89], v77 offset:33984
	ds_read_b128 v[90:93], v77 offset:42432
	ds_read_b128 v[94:97], v77 offset:50880
	ds_read_b128 v[98:101], v77 offset:59328
	s_waitcnt lgkmcnt(3)
; DI f32x4 mfma16(bf16x8 a, bf16x8 b, f32x4 c) { return __builtin_amdgcn_mfma_f32_16x16x32_bf16(a, b, c, 0, 0, 0); }
; template <int NT2>
; DI void glu_prologue(const Params& p, char* lds, int l, int tile0, int tile1) {
;     ...
; #pragma unroll 2
;     for (int ks = 0; ks < 8; ++ks) {
;         bf16x8 bb[2];
; #pragma unroll
;         for (int nt = 0; nt < 2; ++nt) bb[nt] = *(const bf16x8*)(Wg + (wid * 32 + nt * 16 + l15) * 256 + 32 * ks + 8 * quad);
; #pragma unroll
;         for (int tt = 0; tt < NT2; ++tt) {
;             const char* Ys = lds + tt * 33792;
;             bf16x8 a[4];
; #pragma unroll
;             for (int mt = 0; mt < 4; ++mt) a[mt] = *(const bf16x8*)(Ys + (mt * 16 + l15) * 528 + (32 * ks + 8 * quad) * 2);
; #pragma unroll
;             for (int mt = 0; mt < 4; ++mt)
; #pragma unroll
;                 for (int nt = 0; nt < 2; ++nt) acc[tt][mt][nt] = mfma16(bb[nt], a[mt], acc[tt][mt][nt]);
;         }
	v_mfma_f32_16x16x32_bf16 v[34:37], v[128:131], v[86:89], v[34:37]
	v_mfma_f32_16x16x32_bf16 v[26:29], v[132:135], v[86:89], v[26:29]
	s_waitcnt lgkmcnt(2)
	v_mfma_f32_16x16x32_bf16 v[22:25], v[128:131], v[90:93], v[22:25]
	v_mfma_f32_16x16x32_bf16 v[18:21], v[132:135], v[90:93], v[18:21]
	s_waitcnt lgkmcnt(1)
	v_mfma_f32_16x16x32_bf16 v[14:17], v[128:131], v[94:97], v[14:17]
	v_mfma_f32_16x16x32_bf16 v[2:5], v[132:135], v[94:97], v[2:5]
	s_waitcnt lgkmcnt(0)
	v_mfma_f32_16x16x32_bf16 v[10:13], v[128:131], v[98:101], v[10:13]
	v_mfma_f32_16x16x32_bf16 v[6:9], v[132:135], v[98:101], v[6:9]
	s_waitcnt vmcnt(6)
	ds_read_b128 v[86:89], v77 offset:256
	ds_read_b128 v[90:93], v77 offset:8704
	ds_read_b128 v[94:97], v77 offset:17152
	ds_read_b128 v[98:101], v77 offset:25600
	s_waitcnt lgkmcnt(3)
	v_mfma_f32_16x16x32_bf16 v[54:57], v[140:143], v[86:89], v[54:57]
	v_mfma_f32_16x16x32_bf16 v[58:61], v[144:147], v[86:89], v[58:61]
	s_waitcnt lgkmcnt(2)
	v_mfma_f32_16x16x32_bf16 v[68:71], v[140:143], v[90:93], v[68:71]
	v_mfma_f32_16x16x32_bf16 v[50:53], v[144:147], v[90:93], v[50:53]
	s_waitcnt lgkmcnt(1)
	v_mfma_f32_16x16x32_bf16 v[46:49], v[140:143], v[94:97], v[46:49]
	v_mfma_f32_16x16x32_bf16 v[42:45], v[144:147], v[94:97], v[42:45]
	s_waitcnt lgkmcnt(0)
	v_mfma_f32_16x16x32_bf16 v[38:41], v[140:143], v[98:101], v[38:41]
	v_mfma_f32_16x16x32_bf16 v[30:33], v[144:147], v[98:101], v[30:33]
	ds_read_b128 v[86:89], v77 offset:34048
	ds_read_b128 v[90:93], v77 offset:42496
	ds_read_b128 v[94:97], v77 offset:50944
	ds_read_b128 v[98:101], v77 offset:59392
	s_waitcnt lgkmcnt(3)
	v_mfma_f32_16x16x32_bf16 v[34:37], v[140:143], v[86:89], v[34:37]
	v_mfma_f32_16x16x32_bf16 v[26:29], v[144:147], v[86:89], v[26:29]
	s_waitcnt lgkmcnt(2)
	v_mfma_f32_16x16x32_bf16 v[22:25], v[140:143], v[90:93], v[22:25]
	v_mfma_f32_16x16x32_bf16 v[18:21], v[144:147], v[90:93], v[18:21]
	s_waitcnt lgkmcnt(1)
	v_mfma_f32_16x16x32_bf16 v[14:17], v[140:143], v[94:97], v[14:17]
	v_mfma_f32_16x16x32_bf16 v[2:5], v[144:147], v[94:97], v[2:5]
	s_waitcnt lgkmcnt(0)
	v_mfma_f32_16x16x32_bf16 v[10:13], v[140:143], v[98:101], v[10:13]
	v_mfma_f32_16x16x32_bf16 v[6:9], v[144:147], v[98:101], v[6:9]
	s_waitcnt vmcnt(4)
	ds_read_b128 v[86:89], v77 offset:320
	ds_read_b128 v[90:93], v77 offset:8768
	ds_read_b128 v[94:97], v77 offset:17216
	ds_read_b128 v[98:101], v77 offset:25664
	s_waitcnt lgkmcnt(3)
	v_mfma_f32_16x16x32_bf16 v[54:57], v[148:151], v[86:89], v[54:57]
	v_mfma_f32_16x16x32_bf16 v[58:61], v[152:155], v[86:89], v[58:61]
	s_waitcnt lgkmcnt(2)
	v_mfma_f32_16x16x32_bf16 v[68:71], v[148:151], v[90:93], v[68:71]
	v_mfma_f32_16x16x32_bf16 v[50:53], v[152:155], v[90:93], v[50:53]
	s_waitcnt lgkmcnt(1)
	v_mfma_f32_16x16x32_bf16 v[46:49], v[148:151], v[94:97], v[46:49]
	v_mfma_f32_16x16x32_bf16 v[42:45], v[152:155], v[94:97], v[42:45]
	s_waitcnt lgkmcnt(0)
	v_mfma_f32_16x16x32_bf16 v[38:41], v[148:151], v[98:101], v[38:41]
	v_mfma_f32_16x16x32_bf16 v[30:33], v[152:155], v[98:101], v[30:33]
	ds_read_b128 v[86:89], v77 offset:34112
	ds_read_b128 v[90:93], v77 offset:42560
	ds_read_b128 v[94:97], v77 offset:51008
	ds_read_b128 v[98:101], v77 offset:59456
	s_waitcnt lgkmcnt(3)
	v_mfma_f32_16x16x32_bf16 v[34:37], v[148:151], v[86:89], v[34:37]
	v_mfma_f32_16x16x32_bf16 v[26:29], v[152:155], v[86:89], v[26:29]
	s_waitcnt lgkmcnt(2)
	v_mfma_f32_16x16x32_bf16 v[22:25], v[148:151], v[90:93], v[22:25]
	v_mfma_f32_16x16x32_bf16 v[18:21], v[152:155], v[90:93], v[18:21]
	s_waitcnt lgkmcnt(1)
	v_mfma_f32_16x16x32_bf16 v[14:17], v[148:151], v[94:97], v[14:17]
	v_mfma_f32_16x16x32_bf16 v[2:5], v[152:155], v[94:97], v[2:5]
	s_waitcnt lgkmcnt(0)
	v_mfma_f32_16x16x32_bf16 v[10:13], v[148:151], v[98:101], v[10:13]
	v_mfma_f32_16x16x32_bf16 v[6:9], v[152:155], v[98:101], v[6:9]
	s_waitcnt vmcnt(2)
	ds_read_b128 v[86:89], v77 offset:384
	ds_read_b128 v[90:93], v77 offset:8832
	ds_read_b128 v[94:97], v77 offset:17280
	ds_read_b128 v[98:101], v77 offset:25728
	s_waitcnt lgkmcnt(3)
	v_mfma_f32_16x16x32_bf16 v[54:57], v[156:159], v[86:89], v[54:57]
	v_mfma_f32_16x16x32_bf16 v[58:61], v[160:163], v[86:89], v[58:61]
	s_waitcnt lgkmcnt(2)
	v_mfma_f32_16x16x32_bf16 v[68:71], v[156:159], v[90:93], v[68:71]
	v_mfma_f32_16x16x32_bf16 v[50:53], v[160:163], v[90:93], v[50:53]
	s_waitcnt lgkmcnt(1)
	v_mfma_f32_16x16x32_bf16 v[46:49], v[156:159], v[94:97], v[46:49]
	v_mfma_f32_16x16x32_bf16 v[42:45], v[160:163], v[94:97], v[42:45]
	s_waitcnt lgkmcnt(0)
	v_mfma_f32_16x16x32_bf16 v[38:41], v[156:159], v[98:101], v[38:41]
	v_mfma_f32_16x16x32_bf16 v[30:33], v[160:163], v[98:101], v[30:33]
	ds_read_b128 v[86:89], v77 offset:34176
	ds_read_b128 v[90:93], v77 offset:42624
	ds_read_b128 v[94:97], v77 offset:51072
	ds_read_b128 v[98:101], v77 offset:59520
	s_waitcnt lgkmcnt(3)
	v_mfma_f32_16x16x32_bf16 v[34:37], v[156:159], v[86:89], v[34:37]
	v_mfma_f32_16x16x32_bf16 v[26:29], v[160:163], v[86:89], v[26:29]
	s_waitcnt lgkmcnt(2)
	v_mfma_f32_16x16x32_bf16 v[22:25], v[156:159], v[90:93], v[22:25]
	v_mfma_f32_16x16x32_bf16 v[18:21], v[160:163], v[90:93], v[18:21]
	s_waitcnt lgkmcnt(1)
	v_mfma_f32_16x16x32_bf16 v[14:17], v[156:159], v[94:97], v[14:17]
	v_mfma_f32_16x16x32_bf16 v[2:5], v[160:163], v[94:97], v[2:5]
	s_waitcnt lgkmcnt(0)
	v_mfma_f32_16x16x32_bf16 v[10:13], v[156:159], v[98:101], v[10:13]
	v_mfma_f32_16x16x32_bf16 v[6:9], v[160:163], v[98:101], v[6:9]
	s_waitcnt vmcnt(0)
	ds_read_b128 v[86:89], v77 offset:448
	ds_read_b128 v[90:93], v77 offset:8896
	ds_read_b128 v[94:97], v77 offset:17344
	ds_read_b128 v[98:101], v77 offset:25792
	s_waitcnt lgkmcnt(3)
; DI unsigned pk2(float lo, float hi) { const f32x2 v = {lo, hi}; const bf16x2_t b = __builtin_convertvector(v, bf16x2_t); return __builtin_bit_cast(unsigned, b); }
; DI float bf2f(unsigned b) { return __uint_as_float(b << 16); }
; DI float sigmoid_f(float x) { return __builtin_amdgcn_rcpf(1.f + __builtin_amdgcn_exp2f(x * -1.44269504089f)); }
; DI f32x4 mfma16(bf16x8 a, bf16x8 b, f32x4 c) { return __builtin_amdgcn_mfma_f32_16x16x32_bf16(a, b, c, 0, 0, 0); }
; DI size_t y_off(int tok, int col) { return ((size_t)(((tok >> 6) * 32 + (col >> 5)) * 64 + (tok & 63))) * 32 + (col & 31); }
; template <int NT2>
; DI void glu_prologue(const Params& p, char* lds, int l, int tile0, int tile1) {
;     ...
;                 for (int nt = 0; nt < 2; ++nt) acc[tt][mt][nt] = mfma16(bb[nt], a[mt], acc[tt][mt][nt]);
;     ...
;     for (int tt = 0; tt < NT2; ++tt) {
;         const int tile = tt ? tile1 : tile0;
;         const char* Ys = lds + tt * 33792;
;         const bf16_t* sg = WS_PTR(const bf16_t, OFF_SG) + (size_t)tile * 64 * 256;
; #pragma unroll
;         for (int mt = 0; mt < 4; ++mt) {
;             const int tok = mt * 16 + l15;
; #pragma unroll
;             for (int nt = 0; nt < 2; ++nt) {
;                 const int n0 = wid * 32 + nt * 16 + quad * 4;
;                 const f32x4 gb = *(const f32x4*)(p.glu_b + l * 256 + n0);
;                 const u32x2 yv = *(const u32x2*)(Ys + tok * 528 + n0 * 2);
;                 const u32x2 sv = *(const u32x2*)(sg + (size_t)tok * 256 + n0);
;                 float o[4];
;                 o[0] = sigmoid_f(acc[tt][mt][nt][0] + gb[0]) * bf2f(yv[0] & 0xffffu) * bf2f(sv[0] & 0xffffu);
;                 o[1] = sigmoid_f(acc[tt][mt][nt][1] + gb[1]) * bf2f(yv[0] >> 16) * bf2f(sv[0] >> 16);
;                 o[2] = sigmoid_f(acc[tt][mt][nt][2] + gb[2]) * bf2f(yv[1] & 0xffffu) * bf2f(sv[1] & 0xffffu);
;                 o[3] = sigmoid_f(acc[tt][mt][nt][3] + gb[3]) * bf2f(yv[1] >> 16) * bf2f(sv[1] >> 16);
;                 *(u32x2*)(yo + y_off(tile * 64 + tok, 512 + n0)) = (u32x2){pk2(o[0], o[1]), pk2(o[2], o[3])};
	v_mfma_f32_16x16x32_bf16 v[54:57], v[164:167], v[86:89], v[54:57]
	v_mfma_f32_16x16x32_bf16 v[58:61], v[168:171], v[86:89], v[58:61]
	s_waitcnt lgkmcnt(2)
	v_mfma_f32_16x16x32_bf16 v[68:71], v[164:167], v[90:93], v[68:71]
	v_mfma_f32_16x16x32_bf16 v[50:53], v[168:171], v[90:93], v[50:53]
	s_waitcnt lgkmcnt(1)
	v_mfma_f32_16x16x32_bf16 v[46:49], v[164:167], v[94:97], v[46:49]
	v_mfma_f32_16x16x32_bf16 v[42:45], v[168:171], v[94:97], v[42:45]
	s_waitcnt lgkmcnt(0)
	v_mfma_f32_16x16x32_bf16 v[38:41], v[164:167], v[98:101], v[38:41]
	v_mfma_f32_16x16x32_bf16 v[30:33], v[168:171], v[98:101], v[30:33]
	ds_read_b128 v[86:89], v77 offset:34240
	ds_read_b128 v[90:93], v77 offset:42688
	ds_read_b128 v[94:97], v77 offset:51136
	ds_read_b128 v[98:101], v77 offset:59584
	s_waitcnt lgkmcnt(3)
	v_mfma_f32_16x16x32_bf16 v[34:37], v[164:167], v[86:89], v[34:37]
	v_mfma_f32_16x16x32_bf16 v[26:29], v[168:171], v[86:89], v[26:29]
	s_waitcnt lgkmcnt(2)
	v_mfma_f32_16x16x32_bf16 v[22:25], v[164:167], v[90:93], v[22:25]
	v_mfma_f32_16x16x32_bf16 v[18:21], v[168:171], v[90:93], v[18:21]
	s_waitcnt lgkmcnt(1)
	v_mfma_f32_16x16x32_bf16 v[14:17], v[164:167], v[94:97], v[14:17]
	v_mfma_f32_16x16x32_bf16 v[2:5], v[168:171], v[94:97], v[2:5]
	s_waitcnt lgkmcnt(0)
	v_mfma_f32_16x16x32_bf16 v[10:13], v[164:167], v[98:101], v[10:13]
	v_mfma_f32_16x16x32_bf16 v[6:9], v[168:171], v[98:101], v[6:9]
	v_lshlrev_b32_e32 v66, 5, v76
	v_lshlrev_b32_e32 v62, 2, v79
	v_or_b32_e32 v62, v62, v66
	v_ashrrev_i32_e32 v63, 31, v62
	v_lshl_add_u64 v[76:77], v[62:63], 2, s[2:3]
	global_load_dwordx4 v[216:219], v[76:77], off
	v_readlane_b32 s40, v244, 48
	s_add_u32 s8, s40, s8
	v_readlane_b32 s46, v244, 49
	s_addc_u32 s9, s46, s9
	v_lshlrev_b32_e32 v0, 1, v0
	v_lshl_add_u64 v[96:97], s[8:9], 0, v[0:1]
	v_lshlrev_b64 v[80:81], 1, v[62:63]
	v_lshl_add_u64 v[246:247], v[96:97], 0, v[80:81]
	global_load_dwordx2 v[224:225], v[246:247], off
	v_and_b32_e32 v63, 0xffffffc0, v78
	v_add_u32_e32 v86, 0x400, v63
	v_lshl_add_u32 v89, s34, 11, v86
	v_add_u32_e32 v87, 0, v82
	v_or_b32_e32 v82, v89, v84
	v_ashrrev_i32_e32 v63, 31, v66
	v_ashrrev_i32_e32 v83, 31, v82
	v_lshlrev_b32_e32 v90, 1, v62
	v_lshl_add_u64 v[72:73], v[62:63], 2, s[2:3]
	v_lshlrev_b64 v[74:75], 1, v[62:63]
	v_lshlrev_b64 v[62:63], 6, v[82:83]
	v_add_u32_e32 v64, v87, v90
	ds_read2st64_b64 v[64:67], v64 offset1:66
	v_lshlrev_b32_e32 v78, 3, v79
	v_mov_b32_e32 v79, v1
	v_lshl_add_u64 v[62:63], s[54:55], 0, v[62:63]
	v_lshl_add_u64 v[100:101], v[62:63], 0, v[78:79]
	s_waitcnt lgkmcnt(0)
	v_lshlrev_b32_e32 v62, 16, v64
	v_and_b32_e32 v63, 0xffff0000, v64
	v_lshlrev_b32_e32 v64, 16, v65
	v_and_b32_e32 v65, 0xffff0000, v65
	v_add_u32_e32 v91, 0x2100, v87
	s_add_u32 s6, s40, s6
	s_addc_u32 s7, s46, s7
	v_lshl_add_u64 v[246:247], v[96:97], 0, v[74:75]
	global_load_dwordx2 v[226:227], v[246:247], off offset:32
	s_waitcnt vmcnt(2)
	v_add_f32_e32 v54, v54, v216
	v_add_f32_e32 v55, v55, v217
	v_add_f32_e32 v56, v56, v218
	v_add_f32_e32 v57, v57, v219
	v_mul_f32_e32 v82, 0xbfb8aa3b, v54
	v_mul_f32_e32 v83, 0xbfb8aa3b, v55
	v_mul_f32_e32 v56, 0xbfb8aa3b, v56
	v_mul_f32_e32 v57, 0xbfb8aa3b, v57
	v_exp_f32_e32 v82, v82
	v_exp_f32_e32 v83, v83
	v_exp_f32_e32 v56, v56
	v_exp_f32_e32 v57, v57
	v_add_f32_e32 v82, 1.0, v82
	v_add_f32_e32 v83, 1.0, v83
	v_add_f32_e32 v85, 1.0, v56
	v_add_f32_e32 v88, 1.0, v57
	v_rcp_f32_e32 v56, v82
	v_rcp_f32_e32 v57, v83
	v_rcp_f32_e32 v82, v85
	v_rcp_f32_e32 v83, v88
	s_waitcnt vmcnt(1)
	v_lshlrev_b32_e32 v54, 16, v224
	v_and_b32_e32 v55, 0xffff0000, v224
	v_lshlrev_b32_e32 v92, 16, v225
	v_and_b32_e32 v93, 0xffff0000, v225
	v_pk_mul_f32 v[56:57], v[56:57], v[62:63]
	v_pk_mul_f32 v[62:63], v[82:83], v[64:65]
	v_pk_mul_f32 v[54:55], v[56:57], v[54:55]
	v_pk_mul_f32 v[56:57], v[62:63], v[92:93]
	v_cvt_pk_bf16_f32 v54, v54, v55
	v_cvt_pk_bf16_f32 v55, v56, v57
	global_store_dwordx2 v[100:101], v[54:55], off
	global_load_dwordx4 v[220:223], v[72:73], off offset:64
	v_or_b32_e32 v88, 32, v90
	v_add_u32_e32 v54, v87, v88
	ds_read2st64_b64 v[54:57], v54 offset1:66
	v_or_b32_e32 v85, 16, v84
	v_mov_b32_e32 v83, v1
	v_lshlrev_b32_e32 v82, 9, v85
	v_lshl_add_u64 v[94:95], s[8:9], 0, v[82:83]
	s_waitcnt lgkmcnt(0)
	v_lshlrev_b32_e32 v96, 16, v54
	v_and_b32_e32 v97, 0xffff0000, v54
	v_lshlrev_b32_e32 v54, 16, v55
	v_and_b32_e32 v55, 0xffff0000, v55
	v_lshl_add_u64 v[246:247], v[94:95], 0, v[80:81]
	global_load_dwordx2 v[224:225], v[246:247], off
	s_waitcnt vmcnt(1)
	v_add_f32_e32 v62, v58, v220
	v_add_f32_e32 v63, v59, v221
	v_add_f32_e32 v60, v60, v222
	v_add_f32_e32 v61, v61, v223
	v_mul_f32_e32 v62, 0xbfb8aa3b, v62
	v_mul_f32_e32 v63, 0xbfb8aa3b, v63
	v_mul_f32_e32 v60, 0xbfb8aa3b, v60
	v_mul_f32_e32 v61, 0xbfb8aa3b, v61
	v_exp_f32_e32 v62, v62
	v_exp_f32_e32 v63, v63
	v_exp_f32_e32 v60, v60
	v_exp_f32_e32 v61, v61
	v_add_f32_e32 v62, 1.0, v62
	v_add_f32_e32 v63, 1.0, v63
	v_add_f32_e32 v64, 1.0, v60
	v_add_f32_e32 v65, 1.0, v61
	v_rcp_f32_e32 v60, v62
	v_rcp_f32_e32 v61, v63
	v_rcp_f32_e32 v62, v64
	v_rcp_f32_e32 v63, v65
	s_waitcnt vmcnt(1)
	v_lshlrev_b32_e32 v58, 16, v226
	v_and_b32_e32 v59, 0xffff0000, v226
	v_lshlrev_b32_e32 v64, 16, v227
	v_and_b32_e32 v65, 0xffff0000, v227
	v_pk_mul_f32 v[60:61], v[60:61], v[96:97]
	v_pk_mul_f32 v[54:55], v[62:63], v[54:55]
	v_pk_mul_f32 v[58:59], v[60:61], v[58:59]
	v_pk_mul_f32 v[54:55], v[54:55], v[64:65]
	v_cvt_pk_bf16_f32 v58, v58, v59
	v_cvt_pk_bf16_f32 v59, v54, v55
	global_store_dwordx2 v[100:101], v[58:59], off offset:32
	v_add_u32_e32 v58, v91, v90
	ds_read2st64_b64 v[58:61], v58 offset1:66
	v_or_b32_e32 v92, v89, v85
	v_ashrrev_i32_e32 v93, 31, v92
	v_lshlrev_b64 v[92:93], 6, v[92:93]
	v_lshl_add_u64 v[92:93], s[54:55], 0, v[92:93]
	s_waitcnt lgkmcnt(0)
; DI unsigned pk2(float lo, float hi) { const f32x2 v = {lo, hi}; const bf16x2_t b = __builtin_convertvector(v, bf16x2_t); return __builtin_bit_cast(unsigned, b); }
; DI float bf2f(unsigned b) { return __uint_as_float(b << 16); }
; DI float sigmoid_f(float x) { return __builtin_amdgcn_rcpf(1.f + __builtin_amdgcn_exp2f(x * -1.44269504089f)); }
; DI size_t y_off(int tok, int col) { return ((size_t)(((tok >> 6) * 32 + (col >> 5)) * 64 + (tok & 63))) * 32 + (col & 31); }
; template <int NT2>
; DI void glu_prologue(const Params& p, char* lds, int l, int tile0, int tile1) {
;     ...
;         for (int mt = 0; mt < 4; ++mt) {
;             const int tok = mt * 16 + l15;
; #pragma unroll
;             for (int nt = 0; nt < 2; ++nt) {
;                 const int n0 = wid * 32 + nt * 16 + quad * 4;
;                 const f32x4 gb = *(const f32x4*)(p.glu_b + l * 256 + n0);
;                 const u32x2 yv = *(const u32x2*)(Ys + tok * 528 + n0 * 2);
;                 const u32x2 sv = *(const u32x2*)(sg + (size_t)tok * 256 + n0);
;                 float o[4];
;                 o[0] = sigmoid_f(acc[tt][mt][nt][0] + gb[0]) * bf2f(yv[0] & 0xffffu) * bf2f(sv[0] & 0xffffu);
;                 o[1] = sigmoid_f(acc[tt][mt][nt][1] + gb[1]) * bf2f(yv[0] >> 16) * bf2f(sv[0] >> 16);
;                 o[2] = sigmoid_f(acc[tt][mt][nt][2] + gb[2]) * bf2f(yv[1] & 0xffffu) * bf2f(sv[1] & 0xffffu);
;                 o[3] = sigmoid_f(acc[tt][mt][nt][3] + gb[3]) * bf2f(yv[1] >> 16) * bf2f(sv[1] >> 16);
;                 *(u32x2*)(yo + y_off(tile * 64 + tok, 512 + n0)) = (u32x2){pk2(o[0], o[1]), pk2(o[2], o[3])};
	v_lshlrev_b32_e32 v96, 16, v58
	v_and_b32_e32 v97, 0xffff0000, v58
	v_lshlrev_b32_e32 v58, 16, v59
	v_and_b32_e32 v59, 0xffff0000, v59
	v_lshl_add_u64 v[92:93], v[92:93], 0, v[78:79]
	v_lshl_add_u64 v[246:247], v[94:95], 0, v[74:75]
	global_load_dwordx2 v[226:227], v[246:247], off offset:32
	v_add_f32_e32 v68, v68, v216
	v_add_f32_e32 v69, v69, v217
	s_waitcnt vmcnt(2)
	v_lshlrev_b32_e32 v62, 16, v224
	v_and_b32_e32 v63, 0xffff0000, v224
	v_add_f32_e32 v54, v70, v218
	v_add_f32_e32 v64, v71, v219
	v_mul_f32_e32 v65, 0xbfb8aa3b, v68
	v_mul_f32_e32 v68, 0xbfb8aa3b, v69
	v_mul_f32_e32 v54, 0xbfb8aa3b, v54
	v_mul_f32_e32 v64, 0xbfb8aa3b, v64
	v_exp_f32_e32 v65, v65
	v_exp_f32_e32 v68, v68
	v_exp_f32_e32 v54, v54
	v_exp_f32_e32 v64, v64
	v_add_f32_e32 v65, 1.0, v65
	v_add_f32_e32 v68, 1.0, v68
	v_add_f32_e32 v54, 1.0, v54
	v_add_f32_e32 v69, 1.0, v64
	v_rcp_f32_e32 v64, v65
	v_rcp_f32_e32 v65, v68
	v_rcp_f32_e32 v68, v54
	v_rcp_f32_e32 v69, v69
	v_lshlrev_b32_e32 v54, 16, v225
	v_and_b32_e32 v55, 0xffff0000, v225
	v_pk_mul_f32 v[64:65], v[64:65], v[96:97]
	v_pk_mul_f32 v[58:59], v[68:69], v[58:59]
	v_pk_mul_f32 v[62:63], v[64:65], v[62:63]
	v_pk_mul_f32 v[54:55], v[58:59], v[54:55]
	v_cvt_pk_bf16_f32 v58, v62, v63
	v_cvt_pk_bf16_f32 v59, v54, v55
	global_store_dwordx2 v[92:93], v[58:59], off
	v_add_u32_e32 v54, v91, v88
	ds_read2st64_b64 v[62:65], v54 offset1:66
	v_or_b32_e32 v58, 32, v84
	v_mov_b32_e32 v55, v1
	v_lshlrev_b32_e32 v54, 9, v58
	v_lshl_add_u64 v[96:97], s[8:9], 0, v[54:55]
	s_waitcnt lgkmcnt(0)
	v_lshlrev_b32_e32 v98, 16, v62
	v_and_b32_e32 v99, 0xffff0000, v62
	v_lshlrev_b32_e32 v62, 16, v63
	v_and_b32_e32 v63, 0xffff0000, v63
	v_lshl_add_u64 v[246:247], v[96:97], 0, v[80:81]
	global_load_dwordx2 v[224:225], v[246:247], off
	v_add_f32_e32 v59, v50, v220
	v_add_f32_e32 v68, v51, v221
	v_add_f32_e32 v52, v52, v222
	v_add_f32_e32 v53, v53, v223
	v_mul_f32_e32 v59, 0xbfb8aa3b, v59
	v_mul_f32_e32 v68, 0xbfb8aa3b, v68
	v_mul_f32_e32 v52, 0xbfb8aa3b, v52
	v_mul_f32_e32 v53, 0xbfb8aa3b, v53
	v_exp_f32_e32 v59, v59
	v_exp_f32_e32 v68, v68
	v_exp_f32_e32 v52, v52
	v_exp_f32_e32 v53, v53
	v_add_f32_e32 v59, 1.0, v59
	v_add_f32_e32 v68, 1.0, v68
	v_add_f32_e32 v69, 1.0, v52
	v_add_f32_e32 v70, 1.0, v53
	v_rcp_f32_e32 v52, v59
	v_rcp_f32_e32 v53, v68
	v_rcp_f32_e32 v68, v69
	v_rcp_f32_e32 v69, v70
	s_waitcnt vmcnt(2)
	v_lshlrev_b32_e32 v50, 16, v226
	v_and_b32_e32 v51, 0xffff0000, v226
	v_lshlrev_b32_e32 v70, 16, v227
	v_and_b32_e32 v71, 0xffff0000, v227
	v_pk_mul_f32 v[52:53], v[52:53], v[98:99]
	v_pk_mul_f32 v[62:63], v[68:69], v[62:63]
	v_pk_mul_f32 v[50:51], v[52:53], v[50:51]
	v_pk_mul_f32 v[52:53], v[62:63], v[70:71]
	v_cvt_pk_bf16_f32 v50, v50, v51
	v_cvt_pk_bf16_f32 v51, v52, v53
	global_store_dwordx2 v[92:93], v[50:51], off offset:32
	v_add_u32_e32 v59, 0x4200, v87
	v_add_u32_e32 v50, v59, v90
	ds_read2st64_b64 v[50:53], v50 offset1:66
	v_or_b32_e32 v92, v89, v58
	v_ashrrev_i32_e32 v93, 31, v92
	v_lshlrev_b64 v[92:93], 6, v[92:93]
	v_lshl_add_u64 v[92:93], s[54:55], 0, v[92:93]
	s_waitcnt lgkmcnt(0)
	v_lshlrev_b32_e32 v94, 16, v50
	v_and_b32_e32 v95, 0xffff0000, v50
	v_lshlrev_b32_e32 v50, 16, v51
	v_and_b32_e32 v51, 0xffff0000, v51
	v_lshl_add_u64 v[92:93], v[92:93], 0, v[78:79]
	v_add_u32_e32 v87, 0x6300, v87
	v_lshl_add_u64 v[246:247], v[96:97], 0, v[74:75]
	global_load_dwordx2 v[226:227], v[246:247], off offset:32
	v_add_f32_e32 v68, v46, v216
	v_add_f32_e32 v69, v47, v217
	v_add_f32_e32 v48, v48, v218
	v_add_f32_e32 v49, v49, v219
	s_waitcnt vmcnt(2)
	v_lshlrev_b32_e32 v46, 16, v224
	v_and_b32_e32 v47, 0xffff0000, v224
	v_mul_f32_e32 v62, 0xbfb8aa3b, v68
	v_mul_f32_e32 v68, 0xbfb8aa3b, v69
	v_mul_f32_e32 v48, 0xbfb8aa3b, v48
	v_mul_f32_e32 v49, 0xbfb8aa3b, v49
	v_exp_f32_e32 v62, v62
	v_exp_f32_e32 v68, v68
	v_exp_f32_e32 v48, v48
	v_exp_f32_e32 v49, v49
	v_add_f32_e32 v62, 1.0, v62
	v_add_f32_e32 v68, 1.0, v68
	v_add_f32_e32 v69, 1.0, v48
	v_add_f32_e32 v70, 1.0, v49
	v_rcp_f32_e32 v48, v62
	v_rcp_f32_e32 v49, v68
	v_rcp_f32_e32 v68, v69
	v_rcp_f32_e32 v69, v70
	v_lshlrev_b32_e32 v62, 16, v225
	v_and_b32_e32 v63, 0xffff0000, v225
	v_pk_mul_f32 v[48:49], v[48:49], v[94:95]
	v_pk_mul_f32 v[50:51], v[68:69], v[50:51]
	v_pk_mul_f32 v[46:47], v[48:49], v[46:47]
	v_pk_mul_f32 v[48:49], v[50:51], v[62:63]
	v_cvt_pk_bf16_f32 v46, v46, v47
	v_cvt_pk_bf16_f32 v47, v48, v49
	global_store_dwordx2 v[92:93], v[46:47], off
	v_add_u32_e32 v46, v59, v88
	ds_read2st64_b64 v[46:49], v46 offset1:66
	v_or_b32_e32 v59, 48, v84
	v_mov_b32_e32 v51, v1
	v_lshlrev_b32_e32 v50, 9, v59
	v_lshl_add_u64 v[94:95], s[8:9], 0, v[50:51]
	s_waitcnt lgkmcnt(0)
	v_lshlrev_b32_e32 v96, 16, v46
	v_and_b32_e32 v97, 0xffff0000, v46
	v_lshlrev_b32_e32 v46, 16, v47
	v_and_b32_e32 v47, 0xffff0000, v47
	v_lshl_add_u64 v[246:247], v[94:95], 0, v[80:81]
	global_load_dwordx2 v[224:225], v[246:247], off
	v_add_f32_e32 v68, v42, v220
	v_add_f32_e32 v69, v43, v221
	v_add_f32_e32 v44, v44, v222
	v_add_f32_e32 v45, v45, v223
	s_waitcnt vmcnt(2)
	v_lshlrev_b32_e32 v42, 16, v226
	v_and_b32_e32 v43, 0xffff0000, v226
	v_mul_f32_e32 v62, 0xbfb8aa3b, v68
	v_mul_f32_e32 v68, 0xbfb8aa3b, v69
	v_mul_f32_e32 v44, 0xbfb8aa3b, v44
	v_mul_f32_e32 v45, 0xbfb8aa3b, v45
	v_exp_f32_e32 v62, v62
	v_exp_f32_e32 v68, v68
	v_exp_f32_e32 v44, v44
	v_exp_f32_e32 v45, v45
	v_add_f32_e32 v62, 1.0, v62
	v_add_f32_e32 v68, 1.0, v68
	v_add_f32_e32 v69, 1.0, v44
	v_add_f32_e32 v70, 1.0, v45
	v_rcp_f32_e32 v44, v62
	v_rcp_f32_e32 v45, v68
	v_rcp_f32_e32 v68, v69
	v_rcp_f32_e32 v69, v70
	v_lshlrev_b32_e32 v62, 16, v227
	v_and_b32_e32 v63, 0xffff0000, v227
	v_pk_mul_f32 v[44:45], v[44:45], v[96:97]
	v_pk_mul_f32 v[46:47], v[68:69], v[46:47]
	v_pk_mul_f32 v[42:43], v[44:45], v[42:43]
	v_pk_mul_f32 v[44:45], v[46:47], v[62:63]
	v_cvt_pk_bf16_f32 v42, v42, v43
	v_cvt_pk_bf16_f32 v43, v44, v45
	global_store_dwordx2 v[92:93], v[42:43], off offset:32
	v_add_u32_e32 v42, v87, v90
	ds_read2st64_b64 v[42:45], v42 offset1:66
	v_or_b32_e32 v62, v89, v59
	v_ashrrev_i32_e32 v63, 31, v62
	v_lshlrev_b64 v[62:63], 6, v[62:63]
	v_lshl_add_u64 v[62:63], s[54:55], 0, v[62:63]
	s_waitcnt lgkmcnt(0)
; DI unsigned pk2(float lo, float hi) { const f32x2 v = {lo, hi}; const bf16x2_t b = __builtin_convertvector(v, bf16x2_t); return __builtin_bit_cast(unsigned, b); }
; DI float bf2f(unsigned b) { return __uint_as_float(b << 16); }
; DI float sigmoid_f(float x) { return __builtin_amdgcn_rcpf(1.f + __builtin_amdgcn_exp2f(x * -1.44269504089f)); }
; DI size_t y_off(int tok, int col) { return ((size_t)(((tok >> 6) * 32 + (col >> 5)) * 64 + (tok & 63))) * 32 + (col & 31); }
; template <int NT2>
; DI void glu_prologue(const Params& p, char* lds, int l, int tile0, int tile1) {
;     ...
;         for (int mt = 0; mt < 4; ++mt) {
;             const int tok = mt * 16 + l15;
; #pragma unroll
;             for (int nt = 0; nt < 2; ++nt) {
;                 const int n0 = wid * 32 + nt * 16 + quad * 4;
;                 const f32x4 gb = *(const f32x4*)(p.glu_b + l * 256 + n0);
;                 const u32x2 yv = *(const u32x2*)(Ys + tok * 528 + n0 * 2);
;                 const u32x2 sv = *(const u32x2*)(sg + (size_t)tok * 256 + n0);
;                 float o[4];
;                 o[0] = sigmoid_f(acc[tt][mt][nt][0] + gb[0]) * bf2f(yv[0] & 0xffffu) * bf2f(sv[0] & 0xffffu);
;                 o[1] = sigmoid_f(acc[tt][mt][nt][1] + gb[1]) * bf2f(yv[0] >> 16) * bf2f(sv[0] >> 16);
;                 o[2] = sigmoid_f(acc[tt][mt][nt][2] + gb[2]) * bf2f(yv[1] & 0xffffu) * bf2f(sv[1] & 0xffffu);
;                 o[3] = sigmoid_f(acc[tt][mt][nt][3] + gb[3]) * bf2f(yv[1] >> 16) * bf2f(sv[1] >> 16);
;                 *(u32x2*)(yo + y_off(tile * 64 + tok, 512 + n0)) = (u32x2){pk2(o[0], o[1]), pk2(o[2], o[3])};
	v_lshlrev_b32_e32 v90, 16, v42
	v_and_b32_e32 v91, 0xffff0000, v42
	v_lshlrev_b32_e32 v42, 16, v43
	v_and_b32_e32 v43, 0xffff0000, v43
	v_lshl_add_u64 v[62:63], v[62:63], 0, v[78:79]
	v_lshl_add_u64 v[246:247], v[94:95], 0, v[74:75]
	global_load_dwordx2 v[226:227], v[246:247], off offset:32
	v_add_f32_e32 v68, v38, v216
	v_add_f32_e32 v69, v39, v217
	v_add_f32_e32 v40, v40, v218
	v_add_f32_e32 v41, v41, v219
	s_waitcnt vmcnt(2)
	v_lshlrev_b32_e32 v38, 16, v224
	v_and_b32_e32 v39, 0xffff0000, v224
	v_mul_f32_e32 v46, 0xbfb8aa3b, v68
	v_mul_f32_e32 v68, 0xbfb8aa3b, v69
	v_mul_f32_e32 v40, 0xbfb8aa3b, v40
	v_mul_f32_e32 v41, 0xbfb8aa3b, v41
	v_exp_f32_e32 v46, v46
	v_exp_f32_e32 v68, v68
	v_exp_f32_e32 v40, v40
	v_exp_f32_e32 v41, v41
	v_add_f32_e32 v46, 1.0, v46
	v_add_f32_e32 v68, 1.0, v68
	v_add_f32_e32 v69, 1.0, v40
	v_add_f32_e32 v70, 1.0, v41
	v_rcp_f32_e32 v40, v46
	v_rcp_f32_e32 v41, v68
	v_rcp_f32_e32 v68, v69
	v_rcp_f32_e32 v69, v70
	v_lshlrev_b32_e32 v46, 16, v225
	v_and_b32_e32 v47, 0xffff0000, v225
	v_pk_mul_f32 v[40:41], v[40:41], v[90:91]
	v_pk_mul_f32 v[42:43], v[68:69], v[42:43]
	v_pk_mul_f32 v[38:39], v[40:41], v[38:39]
	v_pk_mul_f32 v[40:41], v[42:43], v[46:47]
	v_cvt_pk_bf16_f32 v38, v38, v39
	v_cvt_pk_bf16_f32 v39, v40, v41
	global_store_dwordx2 v[62:63], v[38:39], off
	v_lshl_add_u64 v[46:47], s[6:7], 0, v[0:1]
	v_add_u32_e32 v38, v87, v88
	ds_read2st64_b64 v[38:41], v38 offset1:66
	s_waitcnt lgkmcnt(0)
	v_lshlrev_b32_e32 v88, 16, v38
	v_and_b32_e32 v89, 0xffff0000, v38
	v_lshlrev_b32_e32 v38, 16, v39
	v_and_b32_e32 v39, 0xffff0000, v39
	v_lshl_add_u64 v[246:247], v[46:47], 0, v[80:81]
	global_load_dwordx2 v[224:225], v[246:247], off
	v_add_f32_e32 v0, v30, v220
	v_add_f32_e32 v68, v31, v221
	v_add_f32_e32 v32, v32, v222
	v_add_f32_e32 v33, v33, v223
	s_waitcnt vmcnt(2)
	v_lshlrev_b32_e32 v30, 16, v226
	v_and_b32_e32 v31, 0xffff0000, v226
	v_mul_f32_e32 v0, 0xbfb8aa3b, v0
	v_mul_f32_e32 v42, 0xbfb8aa3b, v68
	v_mul_f32_e32 v32, 0xbfb8aa3b, v32
	v_mul_f32_e32 v33, 0xbfb8aa3b, v33
	v_exp_f32_e32 v0, v0
	v_exp_f32_e32 v42, v42
	v_exp_f32_e32 v32, v32
	v_exp_f32_e32 v33, v33
	v_add_f32_e32 v0, 1.0, v0
	v_add_f32_e32 v42, 1.0, v42
	v_add_f32_e32 v68, 1.0, v32
	v_add_f32_e32 v69, 1.0, v33
	v_rcp_f32_e32 v32, v0
	v_rcp_f32_e32 v33, v42
	v_rcp_f32_e32 v68, v68
	v_rcp_f32_e32 v69, v69
	v_lshlrev_b32_e32 v42, 16, v227
	v_and_b32_e32 v43, 0xffff0000, v227
	v_pk_mul_f32 v[32:33], v[32:33], v[88:89]
	v_pk_mul_f32 v[38:39], v[68:69], v[38:39]
	v_pk_mul_f32 v[30:31], v[32:33], v[30:31]
	v_pk_mul_f32 v[32:33], v[38:39], v[42:43]
	v_cvt_pk_bf16_f32 v30, v30, v31
	v_cvt_pk_bf16_f32 v31, v32, v33
	global_store_dwordx2 v[62:63], v[30:31], off offset:32
	v_lshl_add_u32 v0, s48, 11, v86
	v_or_b32_e32 v42, v0, v84
	v_ashrrev_i32_e32 v43, 31, v42
	v_lshlrev_b32_e32 v62, 16, v66
	v_and_b32_e32 v63, 0xffff0000, v66
	v_lshlrev_b32_e32 v66, 16, v67
	v_and_b32_e32 v67, 0xffff0000, v67
	v_lshlrev_b64 v[42:43], 6, v[42:43]
	v_lshl_add_u64 v[42:43], s[54:55], 0, v[42:43]
	v_lshl_add_u64 v[42:43], v[42:43], 0, v[78:79]
	v_lshl_add_u64 v[246:247], v[46:47], 0, v[74:75]
	global_load_dwordx2 v[226:227], v[246:247], off offset:32
	v_add_f32_e32 v34, v34, v216
	v_add_f32_e32 v35, v35, v217
	v_add_f32_e32 v32, v36, v218
	v_add_f32_e32 v33, v37, v219
	v_mul_f32_e32 v34, 0xbfb8aa3b, v34
	v_mul_f32_e32 v35, 0xbfb8aa3b, v35
	v_mul_f32_e32 v32, 0xbfb8aa3b, v32
	v_mul_f32_e32 v33, 0xbfb8aa3b, v33
	v_exp_f32_e32 v34, v34
	v_exp_f32_e32 v35, v35
	v_exp_f32_e32 v32, v32
	v_exp_f32_e32 v33, v33
	v_add_f32_e32 v34, 1.0, v34
	v_add_f32_e32 v35, 1.0, v35
	v_add_f32_e32 v36, 1.0, v32
	v_add_f32_e32 v37, 1.0, v33
	v_rcp_f32_e32 v32, v34
	v_rcp_f32_e32 v33, v35
	v_rcp_f32_e32 v34, v36
	v_rcp_f32_e32 v35, v37
	s_waitcnt vmcnt(2)
	v_lshlrev_b32_e32 v30, 16, v224
	v_and_b32_e32 v31, 0xffff0000, v224
	v_lshlrev_b32_e32 v36, 16, v225
	v_and_b32_e32 v37, 0xffff0000, v225
	v_pk_mul_f32 v[32:33], v[32:33], v[62:63]
	v_pk_mul_f32 v[34:35], v[34:35], v[66:67]
	v_pk_mul_f32 v[30:31], v[32:33], v[30:31]
	v_pk_mul_f32 v[32:33], v[34:35], v[36:37]
	v_cvt_pk_bf16_f32 v30, v30, v31
	v_cvt_pk_bf16_f32 v31, v32, v33
	global_store_dwordx2 v[42:43], v[30:31], off
	v_lshlrev_b32_e32 v38, 16, v56
	v_and_b32_e32 v39, 0xffff0000, v56
	v_lshlrev_b32_e32 v46, 16, v57
	v_and_b32_e32 v47, 0xffff0000, v57
	v_lshl_add_u64 v[36:37], s[6:7], 0, v[82:83]
	v_lshl_add_u64 v[246:247], v[36:37], 0, v[80:81]
	global_load_dwordx2 v[224:225], v[246:247], off
	v_add_f32_e32 v30, v26, v220
	v_add_f32_e32 v31, v27, v221
	v_add_f32_e32 v28, v28, v222
	v_add_f32_e32 v29, v29, v223
	v_mul_f32_e32 v30, 0xbfb8aa3b, v30
	v_mul_f32_e32 v31, 0xbfb8aa3b, v31
	v_mul_f32_e32 v28, 0xbfb8aa3b, v28
	v_mul_f32_e32 v29, 0xbfb8aa3b, v29
	v_exp_f32_e32 v30, v30
	v_exp_f32_e32 v31, v31
	v_exp_f32_e32 v28, v28
	v_exp_f32_e32 v29, v29
	v_add_f32_e32 v30, 1.0, v30
	v_add_f32_e32 v31, 1.0, v31
	v_add_f32_e32 v32, 1.0, v28
	v_add_f32_e32 v33, 1.0, v29
	v_rcp_f32_e32 v28, v30
	v_rcp_f32_e32 v29, v31
	v_rcp_f32_e32 v30, v32
	v_rcp_f32_e32 v31, v33
	s_waitcnt vmcnt(2)
; DI unsigned pk2(float lo, float hi) { const f32x2 v = {lo, hi}; const bf16x2_t b = __builtin_convertvector(v, bf16x2_t); return __builtin_bit_cast(unsigned, b); }
; DI float bf2f(unsigned b) { return __uint_as_float(b << 16); }
; DI float sigmoid_f(float x) { return __builtin_amdgcn_rcpf(1.f + __builtin_amdgcn_exp2f(x * -1.44269504089f)); }
; DI size_t y_off(int tok, int col) { return ((size_t)(((tok >> 6) * 32 + (col >> 5)) * 64 + (tok & 63))) * 32 + (col & 31); }
; template <int NT2>
; DI void glu_prologue(const Params& p, char* lds, int l, int tile0, int tile1) {
;     ...
;         for (int mt = 0; mt < 4; ++mt) {
;             const int tok = mt * 16 + l15;
; #pragma unroll
;             for (int nt = 0; nt < 2; ++nt) {
;                 const int n0 = wid * 32 + nt * 16 + quad * 4;
;                 const f32x4 gb = *(const f32x4*)(p.glu_b + l * 256 + n0);
;                 const u32x2 yv = *(const u32x2*)(Ys + tok * 528 + n0 * 2);
;                 const u32x2 sv = *(const u32x2*)(sg + (size_t)tok * 256 + n0);
;                 float o[4];
;                 o[0] = sigmoid_f(acc[tt][mt][nt][0] + gb[0]) * bf2f(yv[0] & 0xffffu) * bf2f(sv[0] & 0xffffu);
;                 o[1] = sigmoid_f(acc[tt][mt][nt][1] + gb[1]) * bf2f(yv[0] >> 16) * bf2f(sv[0] >> 16);
;                 o[2] = sigmoid_f(acc[tt][mt][nt][2] + gb[2]) * bf2f(yv[1] & 0xffffu) * bf2f(sv[1] & 0xffffu);
;                 o[3] = sigmoid_f(acc[tt][mt][nt][3] + gb[3]) * bf2f(yv[1] >> 16) * bf2f(sv[1] >> 16);
;                 *(u32x2*)(yo + y_off(tile * 64 + tok, 512 + n0)) = (u32x2){pk2(o[0], o[1]), pk2(o[2], o[3])};
	v_lshlrev_b32_e32 v26, 16, v226
	v_and_b32_e32 v27, 0xffff0000, v226
	v_lshlrev_b32_e32 v32, 16, v227
	v_and_b32_e32 v33, 0xffff0000, v227
	v_pk_mul_f32 v[28:29], v[28:29], v[38:39]
	v_pk_mul_f32 v[30:31], v[30:31], v[46:47]
	v_pk_mul_f32 v[26:27], v[28:29], v[26:27]
	v_pk_mul_f32 v[28:29], v[30:31], v[32:33]
	v_cvt_pk_bf16_f32 v26, v26, v27
	v_cvt_pk_bf16_f32 v27, v28, v29
	global_store_dwordx2 v[42:43], v[26:27], off offset:32
	v_or_b32_e32 v32, v0, v85
	v_ashrrev_i32_e32 v33, 31, v32
	v_lshlrev_b32_e32 v34, 16, v60
	v_and_b32_e32 v35, 0xffff0000, v60
	v_lshlrev_b32_e32 v38, 16, v61
	v_and_b32_e32 v39, 0xffff0000, v61
	v_lshlrev_b64 v[32:33], 6, v[32:33]
	v_lshl_add_u64 v[32:33], s[54:55], 0, v[32:33]
	v_lshl_add_u64 v[32:33], v[32:33], 0, v[78:79]
	v_lshl_add_u64 v[246:247], v[36:37], 0, v[74:75]
	global_load_dwordx2 v[226:227], v[246:247], off offset:32
	v_add_f32_e32 v26, v22, v216
	v_add_f32_e32 v27, v23, v217
	v_add_f32_e32 v24, v24, v218
	v_add_f32_e32 v25, v25, v219
	v_mul_f32_e32 v26, 0xbfb8aa3b, v26
	v_mul_f32_e32 v27, 0xbfb8aa3b, v27
	v_mul_f32_e32 v24, 0xbfb8aa3b, v24
	v_mul_f32_e32 v25, 0xbfb8aa3b, v25
	v_exp_f32_e32 v26, v26
	v_exp_f32_e32 v27, v27
	v_exp_f32_e32 v24, v24
	v_exp_f32_e32 v25, v25
	v_add_f32_e32 v26, 1.0, v26
	v_add_f32_e32 v27, 1.0, v27
	v_add_f32_e32 v28, 1.0, v24
	v_add_f32_e32 v29, 1.0, v25
	v_rcp_f32_e32 v24, v26
	v_rcp_f32_e32 v25, v27
	v_rcp_f32_e32 v26, v28
	v_rcp_f32_e32 v27, v29
	s_waitcnt vmcnt(2)
	v_lshlrev_b32_e32 v22, 16, v224
	v_and_b32_e32 v23, 0xffff0000, v224
	v_lshlrev_b32_e32 v28, 16, v225
	v_and_b32_e32 v29, 0xffff0000, v225
	v_pk_mul_f32 v[24:25], v[24:25], v[34:35]
	v_pk_mul_f32 v[26:27], v[26:27], v[38:39]
	v_pk_mul_f32 v[22:23], v[24:25], v[22:23]
	v_pk_mul_f32 v[24:25], v[26:27], v[28:29]
	v_cvt_pk_bf16_f32 v22, v22, v23
	v_cvt_pk_bf16_f32 v23, v24, v25
	global_store_dwordx2 v[32:33], v[22:23], off
	v_lshlrev_b32_e32 v30, 16, v64
	v_and_b32_e32 v31, 0xffff0000, v64
	v_lshlrev_b32_e32 v34, 16, v65
	v_and_b32_e32 v35, 0xffff0000, v65
	v_lshl_add_u64 v[28:29], s[6:7], 0, v[54:55]
	v_lshl_add_u64 v[246:247], v[28:29], 0, v[80:81]
	global_load_dwordx2 v[224:225], v[246:247], off
	v_add_f32_e32 v22, v18, v220
	v_add_f32_e32 v23, v19, v221
	v_add_f32_e32 v20, v20, v222
	v_add_f32_e32 v21, v21, v223
	v_mul_f32_e32 v22, 0xbfb8aa3b, v22
	v_mul_f32_e32 v23, 0xbfb8aa3b, v23
	v_mul_f32_e32 v20, 0xbfb8aa3b, v20
	v_mul_f32_e32 v21, 0xbfb8aa3b, v21
	v_exp_f32_e32 v22, v22
	v_exp_f32_e32 v23, v23
	v_exp_f32_e32 v20, v20
	v_exp_f32_e32 v21, v21
	v_add_f32_e32 v22, 1.0, v22
	v_add_f32_e32 v23, 1.0, v23
	v_add_f32_e32 v24, 1.0, v20
	v_add_f32_e32 v25, 1.0, v21
	v_rcp_f32_e32 v20, v22
	v_rcp_f32_e32 v21, v23
	v_rcp_f32_e32 v22, v24
	v_rcp_f32_e32 v23, v25
	s_waitcnt vmcnt(2)
	v_lshlrev_b32_e32 v18, 16, v226
	v_and_b32_e32 v19, 0xffff0000, v226
	v_lshlrev_b32_e32 v24, 16, v227
	v_and_b32_e32 v25, 0xffff0000, v227
	v_pk_mul_f32 v[20:21], v[20:21], v[30:31]
	v_pk_mul_f32 v[22:23], v[22:23], v[34:35]
	v_pk_mul_f32 v[18:19], v[20:21], v[18:19]
	v_pk_mul_f32 v[20:21], v[22:23], v[24:25]
	v_cvt_pk_bf16_f32 v18, v18, v19
	v_cvt_pk_bf16_f32 v19, v20, v21
	global_store_dwordx2 v[32:33], v[18:19], off offset:32
	v_or_b32_e32 v24, v0, v58
	v_ashrrev_i32_e32 v25, 31, v24
	v_lshlrev_b32_e32 v26, 16, v52
	v_and_b32_e32 v27, 0xffff0000, v52
	v_lshlrev_b32_e32 v30, 16, v53
	v_and_b32_e32 v31, 0xffff0000, v53
	v_lshlrev_b64 v[24:25], 6, v[24:25]
	v_lshl_add_u64 v[24:25], s[54:55], 0, v[24:25]
	v_lshl_add_u64 v[24:25], v[24:25], 0, v[78:79]
	v_lshl_add_u64 v[246:247], v[28:29], 0, v[74:75]
	global_load_dwordx2 v[226:227], v[246:247], off offset:32
	v_add_f32_e32 v18, v14, v216
	v_add_f32_e32 v19, v15, v217
	v_add_f32_e32 v16, v16, v218
	v_add_f32_e32 v17, v17, v219
	v_mul_f32_e32 v18, 0xbfb8aa3b, v18
	v_mul_f32_e32 v19, 0xbfb8aa3b, v19
	v_mul_f32_e32 v16, 0xbfb8aa3b, v16
	v_mul_f32_e32 v17, 0xbfb8aa3b, v17
	v_exp_f32_e32 v18, v18
	v_exp_f32_e32 v19, v19
	v_exp_f32_e32 v16, v16
	v_exp_f32_e32 v17, v17
	v_add_f32_e32 v18, 1.0, v18
	v_add_f32_e32 v19, 1.0, v19
	v_add_f32_e32 v20, 1.0, v16
	v_add_f32_e32 v21, 1.0, v17
	v_rcp_f32_e32 v16, v18
	v_rcp_f32_e32 v17, v19
	v_rcp_f32_e32 v18, v20
	v_rcp_f32_e32 v19, v21
	s_waitcnt vmcnt(2)
; DI unsigned pk2(float lo, float hi) { const f32x2 v = {lo, hi}; const bf16x2_t b = __builtin_convertvector(v, bf16x2_t); return __builtin_bit_cast(unsigned, b); }
; DI float bf2f(unsigned b) { return __uint_as_float(b << 16); }
; DI float sigmoid_f(float x) { return __builtin_amdgcn_rcpf(1.f + __builtin_amdgcn_exp2f(x * -1.44269504089f)); }
; template <int N> DI void wait_vm() { asm volatile("s_waitcnt vmcnt(%0)" ::"n"(N) : "memory"); }
; DI size_t y_off(int tok, int col) { return ((size_t)(((tok >> 6) * 32 + (col >> 5)) * 64 + (tok & 63))) * 32 + (col & 31); }
; template <int NT2>
; DI void glu_prologue(const Params& p, char* lds, int l, int tile0, int tile1) {
;     ...
;         for (int mt = 0; mt < 4; ++mt) {
;             const int tok = mt * 16 + l15;
; #pragma unroll
;             for (int nt = 0; nt < 2; ++nt) {
;                 const int n0 = wid * 32 + nt * 16 + quad * 4;
;                 const f32x4 gb = *(const f32x4*)(p.glu_b + l * 256 + n0);
;                 const u32x2 yv = *(const u32x2*)(Ys + tok * 528 + n0 * 2);
;                 const u32x2 sv = *(const u32x2*)(sg + (size_t)tok * 256 + n0);
;                 float o[4];
;                 o[0] = sigmoid_f(acc[tt][mt][nt][0] + gb[0]) * bf2f(yv[0] & 0xffffu) * bf2f(sv[0] & 0xffffu);
;                 o[1] = sigmoid_f(acc[tt][mt][nt][1] + gb[1]) * bf2f(yv[0] >> 16) * bf2f(sv[0] >> 16);
;                 o[2] = sigmoid_f(acc[tt][mt][nt][2] + gb[2]) * bf2f(yv[1] & 0xffffu) * bf2f(sv[1] & 0xffffu);
;                 o[3] = sigmoid_f(acc[tt][mt][nt][3] + gb[3]) * bf2f(yv[1] >> 16) * bf2f(sv[1] >> 16);
;                 *(u32x2*)(yo + y_off(tile * 64 + tok, 512 + n0)) = (u32x2){pk2(o[0], o[1]), pk2(o[2], o[3])};
;             }
;         }
;     }
;     wait_vm<0>();
	v_lshlrev_b32_e32 v14, 16, v224
	v_and_b32_e32 v15, 0xffff0000, v224
	v_lshlrev_b32_e32 v20, 16, v225
	v_and_b32_e32 v21, 0xffff0000, v225
	v_pk_mul_f32 v[16:17], v[16:17], v[26:27]
	v_pk_mul_f32 v[18:19], v[18:19], v[30:31]
	v_pk_mul_f32 v[14:15], v[16:17], v[14:15]
	v_pk_mul_f32 v[16:17], v[18:19], v[20:21]
	v_cvt_pk_bf16_f32 v14, v14, v15
	v_cvt_pk_bf16_f32 v15, v16, v17
	global_store_dwordx2 v[24:25], v[14:15], off
	v_lshlrev_b32_e32 v22, 16, v48
	v_and_b32_e32 v23, 0xffff0000, v48
	v_lshlrev_b32_e32 v26, 16, v49
	v_and_b32_e32 v27, 0xffff0000, v49
	v_lshl_add_u64 v[20:21], s[6:7], 0, v[50:51]
	v_lshl_add_u64 v[246:247], v[20:21], 0, v[80:81]
	global_load_dwordx2 v[224:225], v[246:247], off
	v_add_f32_e32 v14, v2, v220
	v_add_f32_e32 v15, v3, v221
	v_add_f32_e32 v4, v4, v222
	v_add_f32_e32 v5, v5, v223
	v_mul_f32_e32 v14, 0xbfb8aa3b, v14
	v_mul_f32_e32 v15, 0xbfb8aa3b, v15
	v_mul_f32_e32 v4, 0xbfb8aa3b, v4
	v_mul_f32_e32 v5, 0xbfb8aa3b, v5
	v_exp_f32_e32 v14, v14
	v_exp_f32_e32 v15, v15
	v_exp_f32_e32 v4, v4
	v_exp_f32_e32 v5, v5
	v_add_f32_e32 v14, 1.0, v14
	v_add_f32_e32 v15, 1.0, v15
	v_add_f32_e32 v16, 1.0, v4
	v_add_f32_e32 v17, 1.0, v5
	v_rcp_f32_e32 v4, v14
	v_rcp_f32_e32 v5, v15
	v_rcp_f32_e32 v14, v16
	v_rcp_f32_e32 v15, v17
	s_waitcnt vmcnt(2)
	v_lshlrev_b32_e32 v2, 16, v226
	v_and_b32_e32 v3, 0xffff0000, v226
	v_lshlrev_b32_e32 v16, 16, v227
	v_and_b32_e32 v17, 0xffff0000, v227
	v_pk_mul_f32 v[4:5], v[4:5], v[22:23]
	v_pk_mul_f32 v[14:15], v[14:15], v[26:27]
	v_pk_mul_f32 v[2:3], v[4:5], v[2:3]
	v_pk_mul_f32 v[4:5], v[14:15], v[16:17]
	v_cvt_pk_bf16_f32 v2, v2, v3
	v_cvt_pk_bf16_f32 v3, v4, v5
	global_store_dwordx2 v[24:25], v[2:3], off offset:32
	v_or_b32_e32 v16, v0, v59
	v_ashrrev_i32_e32 v17, 31, v16
	v_lshlrev_b32_e32 v18, 16, v44
	v_and_b32_e32 v19, 0xffff0000, v44
	v_lshlrev_b32_e32 v22, 16, v45
	v_and_b32_e32 v23, 0xffff0000, v45
	v_lshlrev_b64 v[16:17], 6, v[16:17]
	v_lshl_add_u64 v[16:17], s[54:55], 0, v[16:17]
	v_lshl_add_u64 v[16:17], v[16:17], 0, v[78:79]
	v_lshl_add_u64 v[246:247], v[20:21], 0, v[74:75]
	global_load_dwordx2 v[226:227], v[246:247], off offset:32
	v_add_f32_e32 v0, v10, v216
	v_add_f32_e32 v10, v11, v217
	v_add_f32_e32 v4, v12, v218
	v_add_f32_e32 v5, v13, v219
	v_mul_f32_e32 v0, 0xbfb8aa3b, v0
	v_mul_f32_e32 v10, 0xbfb8aa3b, v10
	v_mul_f32_e32 v4, 0xbfb8aa3b, v4
	v_mul_f32_e32 v5, 0xbfb8aa3b, v5
	v_exp_f32_e32 v0, v0
	v_exp_f32_e32 v10, v10
	v_exp_f32_e32 v4, v4
	v_exp_f32_e32 v5, v5
	v_add_f32_e32 v0, 1.0, v0
	v_add_f32_e32 v10, 1.0, v10
	v_add_f32_e32 v11, 1.0, v4
	v_add_f32_e32 v12, 1.0, v5
	v_rcp_f32_e32 v4, v0
	v_rcp_f32_e32 v5, v10
	v_rcp_f32_e32 v10, v11
	v_rcp_f32_e32 v11, v12
	s_waitcnt vmcnt(2)
	v_lshlrev_b32_e32 v2, 16, v224
	v_and_b32_e32 v3, 0xffff0000, v224
	v_lshlrev_b32_e32 v12, 16, v225
	v_and_b32_e32 v13, 0xffff0000, v225
	v_pk_mul_f32 v[4:5], v[4:5], v[18:19]
	v_pk_mul_f32 v[10:11], v[10:11], v[22:23]
	v_pk_mul_f32 v[2:3], v[4:5], v[2:3]
	v_pk_mul_f32 v[4:5], v[10:11], v[12:13]
	v_cvt_pk_bf16_f32 v2, v2, v3
	v_cvt_pk_bf16_f32 v3, v4, v5
	global_store_dwordx2 v[16:17], v[2:3], off
	v_lshlrev_b32_e32 v12, 16, v40
	v_and_b32_e32 v13, 0xffff0000, v40
	v_lshlrev_b32_e32 v14, 16, v41
	v_and_b32_e32 v15, 0xffff0000, v41
	v_add_f32_e32 v0, v6, v220
	v_add_f32_e32 v6, v7, v221
	v_add_f32_e32 v4, v8, v222
	v_add_f32_e32 v5, v9, v223
	v_mul_f32_e32 v0, 0xbfb8aa3b, v0
	v_mul_f32_e32 v6, 0xbfb8aa3b, v6
	v_mul_f32_e32 v4, 0xbfb8aa3b, v4
	v_mul_f32_e32 v5, 0xbfb8aa3b, v5
	v_exp_f32_e32 v0, v0
	v_exp_f32_e32 v6, v6
	v_exp_f32_e32 v4, v4
	v_exp_f32_e32 v5, v5
	v_add_f32_e32 v0, 1.0, v0
	v_add_f32_e32 v6, 1.0, v6
	v_add_f32_e32 v7, 1.0, v4
	v_add_f32_e32 v8, 1.0, v5
	v_rcp_f32_e32 v4, v0
	v_rcp_f32_e32 v5, v6
	v_rcp_f32_e32 v6, v7
	v_rcp_f32_e32 v7, v8
	s_waitcnt vmcnt(1)
	v_lshlrev_b32_e32 v2, 16, v226
	v_and_b32_e32 v3, 0xffff0000, v226
	v_lshlrev_b32_e32 v8, 16, v227
	v_and_b32_e32 v9, 0xffff0000, v227
	v_pk_mul_f32 v[4:5], v[4:5], v[12:13]
	v_pk_mul_f32 v[6:7], v[6:7], v[14:15]
	v_pk_mul_f32 v[2:3], v[4:5], v[2:3]
	v_pk_mul_f32 v[4:5], v[6:7], v[8:9]
	v_cvt_pk_bf16_f32 v2, v2, v3
	v_cvt_pk_bf16_f32 v3, v4, v5
	global_store_dwordx2 v[16:17], v[2:3], off offset:32
	s_waitcnt vmcnt(0)
